# RWKV output stage (groupnorm+gate): four rows' wave reductions interleaved, LDS reads hoisted, dead denorm-rescale path removed
# speedup vs baseline: 1.0033x; 1.0033x over previous
.LBB0_577:
	s_and_saveexec_b64 s[0:1], s[4:5]
	s_xor_b64 s[20:21], exec, s[0:1]
	s_cbranch_execz .LBB0_595
	s_cmp_lg_u32 s18, 0
	s_cselect_b64 s[22:23], -1, 0
	s_cmp_eq_u32 s18, 0
	s_cbranch_scc1 .LBB0_580
	s_andn2_b32 s1, 1, s25
	v_lshlrev_b32_e32 v1, 2, v85
	s_lshl_b32 s0, s1, 12
	v_lshlrev_b32_e32 v2, 2, v86
	s_add_i32 s27, s0, 0
	v_lshlrev_b32_e32 v3, 2, v87
	s_mul_i32 s0, s1, 0x5000
	v_lshlrev_b32_e32 v36, 2, v88
	s_add_i32 s26, s27, s0
	s_lshl_b32 s1, s1, 6
	v_add_u32_e32 v37, s27, v1
	v_add_u32_e32 v38, s27, v2
	v_add_u32_e32 v39, s27, v3
	v_add_u32_e32 v40, s27, v36
	ds_read2st64_b32 v[216:217], v37 offset0:192 offset1:224
	ds_read2st64_b32 v[218:219], v38 offset0:192 offset1:224
	ds_read2st64_b32 v[220:221], v39 offset0:192 offset1:224
	ds_read2st64_b32 v[222:223], v40 offset0:192 offset1:224
	v_add_u32_e32 v1, s26, v1
	v_add_u32_e32 v2, s26, v2
	v_add_u32_e32 v3, s26, v3
	v_add_u32_e32 v36, s26, v36
	v_lshl_add_u32 v41, v84, 2, s1
	ds_read_b32 v208, v1 offset:20480
	ds_read_b32 v209, v2 offset:20480
	ds_read_b32 v210, v3 offset:20480
	ds_read_b32 v211, v36 offset:20480
	v_add_u32_e32 v41, 0x10000, v41
	ds_read_b128 v[212:215], v41
	s_mov_b32 s34, 0x45800000
	s_waitcnt lgkmcnt(5)
	v_add_f32_dpp v200, v216, v216 quad_perm:[1,0,3,2] row_mask:0xf bank_mask:0xf bound_ctrl:1
	v_add_f32_dpp v201, v218, v218 quad_perm:[1,0,3,2] row_mask:0xf bank_mask:0xf bound_ctrl:1
	v_add_f32_dpp v202, v220, v220 quad_perm:[1,0,3,2] row_mask:0xf bank_mask:0xf bound_ctrl:1
	v_add_f32_dpp v203, v222, v222 quad_perm:[1,0,3,2] row_mask:0xf bank_mask:0xf bound_ctrl:1
	v_mul_f32_e32 v204, 0xbfb8aa3b, v217
	v_mul_f32_e32 v205, 0xbfb8aa3b, v219
	v_add_f32_dpp v200, v200, v200 quad_perm:[2,3,0,1] row_mask:0xf bank_mask:0xf bound_ctrl:1
	v_add_f32_dpp v201, v201, v201 quad_perm:[2,3,0,1] row_mask:0xf bank_mask:0xf bound_ctrl:1
	v_add_f32_dpp v202, v202, v202 quad_perm:[2,3,0,1] row_mask:0xf bank_mask:0xf bound_ctrl:1
	v_add_f32_dpp v203, v203, v203 quad_perm:[2,3,0,1] row_mask:0xf bank_mask:0xf bound_ctrl:1
	v_mul_f32_e32 v206, 0xbfb8aa3b, v221
	v_mul_f32_e32 v207, 0xbfb8aa3b, v223
	v_add_f32_dpp v200, v200, v200 row_half_mirror row_mask:0xf bank_mask:0xf bound_ctrl:1
	v_add_f32_dpp v201, v201, v201 row_half_mirror row_mask:0xf bank_mask:0xf bound_ctrl:1
	v_add_f32_dpp v202, v202, v202 row_half_mirror row_mask:0xf bank_mask:0xf bound_ctrl:1
	v_add_f32_dpp v203, v203, v203 row_half_mirror row_mask:0xf bank_mask:0xf bound_ctrl:1
	v_exp_f32_e32 v204, v204
	v_exp_f32_e32 v205, v205
	v_add_f32_dpp v200, v200, v200 row_mirror row_mask:0xf bank_mask:0xf bound_ctrl:1
	v_add_f32_dpp v201, v201, v201 row_mirror row_mask:0xf bank_mask:0xf bound_ctrl:1
	v_add_f32_dpp v202, v202, v202 row_mirror row_mask:0xf bank_mask:0xf bound_ctrl:1
	v_add_f32_dpp v203, v203, v203 row_mirror row_mask:0xf bank_mask:0xf bound_ctrl:1
	v_exp_f32_e32 v206, v206
	v_exp_f32_e32 v207, v207
	v_add_f32_dpp v200, v200, v200 row_bcast:15 row_mask:0xa bank_mask:0xf
	v_add_f32_dpp v201, v201, v201 row_bcast:15 row_mask:0xa bank_mask:0xf
	v_add_f32_dpp v202, v202, v202 row_bcast:15 row_mask:0xa bank_mask:0xf
	v_add_f32_dpp v203, v203, v203 row_bcast:15 row_mask:0xa bank_mask:0xf
	v_mov_b32_e32 v2, 0x3c800000
	v_add_f32_dpp v200, v200, v200 row_bcast:31 row_mask:0xc bank_mask:0xf
	v_add_f32_dpp v201, v201, v201 row_bcast:31 row_mask:0xc bank_mask:0xf
	v_add_f32_dpp v202, v202, v202 row_bcast:31 row_mask:0xc bank_mask:0xf
	v_add_f32_dpp v203, v203, v203 row_bcast:31 row_mask:0xc bank_mask:0xf
	v_pk_add_f32 v[204:205], v[204:205], 1.0 op_sel_hi:[1,0]
	v_pk_add_f32 v[206:207], v[206:207], 1.0 op_sel_hi:[1,0]
	v_readlane_b32 s0, v200, 63
	v_readlane_b32 s1, v201, 63
	v_readlane_b32 s30, v202, 63
	v_readlane_b32 s31, v203, 63
	v_rcp_f32_e32 v204, v204
	v_rcp_f32_e32 v205, v205
	v_fma_f32 v224, -s0, v2, v216
	v_fma_f32 v225, -s1, v2, v218
	v_fma_f32 v226, -s30, v2, v220
	v_fma_f32 v227, -s31, v2, v222
	v_pk_mul_f32 v[200:201], v[224:225], v[224:225]
	v_pk_mul_f32 v[202:203], v[226:227], v[226:227]
	v_rcp_f32_e32 v206, v206
	v_rcp_f32_e32 v207, v207
	v_add_f32_dpp v200, v200, v200 quad_perm:[1,0,3,2] row_mask:0xf bank_mask:0xf bound_ctrl:1
	v_add_f32_dpp v201, v201, v201 quad_perm:[1,0,3,2] row_mask:0xf bank_mask:0xf bound_ctrl:1
	v_add_f32_dpp v202, v202, v202 quad_perm:[1,0,3,2] row_mask:0xf bank_mask:0xf bound_ctrl:1
	v_add_f32_dpp v203, v203, v203 quad_perm:[1,0,3,2] row_mask:0xf bank_mask:0xf bound_ctrl:1
	v_mul_f32_e32 v204, v217, v204
	v_mul_f32_e32 v205, v219, v205
	v_add_f32_dpp v200, v200, v200 quad_perm:[2,3,0,1] row_mask:0xf bank_mask:0xf bound_ctrl:1
	v_add_f32_dpp v201, v201, v201 quad_perm:[2,3,0,1] row_mask:0xf bank_mask:0xf bound_ctrl:1
	v_add_f32_dpp v202, v202, v202 quad_perm:[2,3,0,1] row_mask:0xf bank_mask:0xf bound_ctrl:1
	v_add_f32_dpp v203, v203, v203 quad_perm:[2,3,0,1] row_mask:0xf bank_mask:0xf bound_ctrl:1
	v_mul_f32_e32 v206, v221, v206
	v_mul_f32_e32 v207, v223, v207
	v_add_f32_dpp v200, v200, v200 row_half_mirror row_mask:0xf bank_mask:0xf bound_ctrl:1
	v_add_f32_dpp v201, v201, v201 row_half_mirror row_mask:0xf bank_mask:0xf bound_ctrl:1
	v_add_f32_dpp v202, v202, v202 row_half_mirror row_mask:0xf bank_mask:0xf bound_ctrl:1
	v_add_f32_dpp v203, v203, v203 row_half_mirror row_mask:0xf bank_mask:0xf bound_ctrl:1
	v_mov_b32_e32 v3, 0x3a27c5ac
	v_add_f32_dpp v200, v200, v200 row_mirror row_mask:0xf bank_mask:0xf bound_ctrl:1
	v_add_f32_dpp v201, v201, v201 row_mirror row_mask:0xf bank_mask:0xf bound_ctrl:1
	v_add_f32_dpp v202, v202, v202 row_mirror row_mask:0xf bank_mask:0xf bound_ctrl:1
	v_add_f32_dpp v203, v203, v203 row_mirror row_mask:0xf bank_mask:0xf bound_ctrl:1
	v_add_f32_dpp v200, v200, v200 row_bcast:15 row_mask:0xa bank_mask:0xf
	v_add_f32_dpp v201, v201, v201 row_bcast:15 row_mask:0xa bank_mask:0xf
	v_add_f32_dpp v202, v202, v202 row_bcast:15 row_mask:0xa bank_mask:0xf
	v_add_f32_dpp v203, v203, v203 row_bcast:15 row_mask:0xa bank_mask:0xf
	v_add_f32_dpp v200, v200, v200 row_bcast:31 row_mask:0xc bank_mask:0xf
	v_add_f32_dpp v201, v201, v201 row_bcast:31 row_mask:0xc bank_mask:0xf
	v_add_f32_dpp v202, v202, v202 row_bcast:31 row_mask:0xc bank_mask:0xf
	v_add_f32_dpp v203, v203, v203 row_bcast:31 row_mask:0xc bank_mask:0xf
	s_nop 0
	v_readlane_b32 s0, v200, 63
	v_readlane_b32 s1, v201, 63
	v_readlane_b32 s30, v202, 63
	v_readlane_b32 s31, v203, 63
	v_fma_f32 v200, s0, v2, v3
	v_fma_f32 v201, s1, v2, v3
	v_fma_f32 v202, s30, v2, v3
	v_fma_f32 v203, s31, v2, v3
	v_rsq_f32_e32 v200, v200
	v_rsq_f32_e32 v201, v201
	v_rsq_f32_e32 v202, v202
	v_rsq_f32_e32 v203, v203
	s_movk_i32 s30, 0x7fff
	s_mov_b32 s31, 0x7060302
	v_pk_mul_f32 v[224:225], v[224:225], v[200:201]
	v_pk_mul_f32 v[226:227], v[226:227], v[202:203]
	v_pk_fma_f32 v[224:225], v[50:51], v[224:225], v[48:49]
	v_pk_fma_f32 v[226:227], v[50:51], v[226:227], v[48:49]
	s_waitcnt lgkmcnt(0)
	v_pk_fma_f32 v[224:225], v[212:213], v[208:209], v[224:225]
	v_pk_fma_f32 v[226:227], v[214:215], v[210:211], v[226:227]
	v_pk_mul_f32 v[224:225], v[204:205], v[224:225]
	v_pk_mul_f32 v[226:227], v[206:207], v[226:227]
	s_nop 1
	v_and_b32_sdwa v1, v225, v190 dst_sel:DWORD dst_unused:UNUSED_PAD src0_sel:WORD_1 src1_sel:DWORD
	v_and_b32_sdwa v2, v224, v190 dst_sel:DWORD dst_unused:UNUSED_PAD src0_sel:WORD_1 src1_sel:DWORD
	v_and_b32_sdwa v3, v227, v190 dst_sel:DWORD dst_unused:UNUSED_PAD src0_sel:WORD_1 src1_sel:DWORD
	v_and_b32_sdwa v36, v226, v190 dst_sel:DWORD dst_unused:UNUSED_PAD src0_sel:WORD_1 src1_sel:DWORD
	v_add3_u32 v2, v224, v2, s30
	v_add3_u32 v1, v225, v1, s30
	v_add3_u32 v36, v226, v36, s30
	v_add3_u32 v3, v227, v3, s30
	v_perm_b32 v149, v1, v2, s31
	v_perm_b32 v150, v3, v36, s31
